# MoBA unit-level de-serialisation: gating k-mean fragment reads issued up front, the eight lane^32 exchanges issued together with counted waits, attn_store second-half read-backs issued together
# baseline (speedup 1.0000x reference)
.LBB0_52:
	v_lshlrev_b64 v[64:65], 11, v[130:131]
	v_lshl_add_u64 v[64:65], s[82:83], 0, v[64:65]
	v_cmp_lt_i32_e32 vcc, v234, v228
	v_lshl_add_u64 v[66:67], s[0:1], 1, v[64:65]
	v_lshl_add_u32 v68, v145, 12, s45
	v_cndmask_b32_e32 v64, v227, v234, vcc
	v_lshlrev_b32_e32 v64, 2, v64
	ds_bpermute_b32 v64, v64, v168
	s_barrier
	s_add_i32 s2, s2, s80
	s_cmpk_gt_i32 s2, 0x1ff
	s_waitcnt lgkmcnt(0)
	v_add_f32_e32 v64, v168, v64
	v_div_scale_f32 v65, s[0:1], v64, v64, 1.0
	v_rcp_f32_e32 v69, v65
	s_movk_i32 s0, 0x50
	v_fma_f32 v70, -v65, v69, 1.0
	v_fmac_f32_e32 v69, v70, v69
	v_div_scale_f32 v70, vcc, 1.0, v64, 1.0
	v_mul_f32_e32 v71, v70, v69
	v_fma_f32 v72, -v65, v71, v70
	v_fmac_f32_e32 v71, v72, v69
	v_fma_f32 v65, -v65, v71, v70
	v_div_fmas_f32 v65, v65, v69, v71
	v_div_fixup_f32 v64, v65, v64, 1.0
	v_lshlrev_b32_e32 v65, 7, v144
	v_and_b32_e32 v65, 0xf80, v65
	v_and_b32_e32 v69, 8, v165
	v_add3_u32 v65, v68, v65, v69
	v_pk_mul_f32 v[48:49], v[48:49], v[64:65] op_sel_hi:[1,0]
	v_pk_mul_f32 v[50:51], v[50:51], v[64:65] op_sel_hi:[1,0]
	v_cvt_pk_bf16_f32 v48, v48, v49
	v_cvt_pk_bf16_f32 v49, v50, v51
	v_lshlrev_b32_e32 v50, 4, v143
	v_and_b32_e32 v72, 0x70, v50
	v_add_u32_e32 v73, v65, v72
	ds_write_b64 v73, v[48:49]
	v_pk_mul_f32 v[48:49], v[52:53], v[64:65] op_sel_hi:[1,0]
	v_pk_mul_f32 v[50:51], v[54:55], v[64:65] op_sel_hi:[1,0]
	v_cvt_pk_bf16_f32 v48, v48, v49
	v_cvt_pk_bf16_f32 v49, v50, v51
	v_xad_u32 v52, v72, 16, v65
	ds_write_b64 v52, v[48:49]
	v_pk_mul_f32 v[48:49], v[56:57], v[64:65] op_sel_hi:[1,0]
	v_pk_mul_f32 v[50:51], v[58:59], v[64:65] op_sel_hi:[1,0]
	v_cvt_pk_bf16_f32 v48, v48, v49
	v_cvt_pk_bf16_f32 v49, v50, v51
	v_xad_u32 v53, v72, 32, v65
	ds_write_b64 v53, v[48:49]
	v_pk_mul_f32 v[48:49], v[60:61], v[64:65] op_sel_hi:[1,0]
	v_pk_mul_f32 v[50:51], v[62:63], v[64:65] op_sel_hi:[1,0]
	v_cvt_pk_bf16_f32 v48, v48, v49
	v_cvt_pk_bf16_f32 v49, v50, v51
	v_xad_u32 v50, v72, 48, v65
	v_pk_mul_f32 v[32:33], v[32:33], v[64:65] op_sel_hi:[1,0]
	v_pk_mul_f32 v[34:35], v[34:35], v[64:65] op_sel_hi:[1,0]
	ds_write_b64 v50, v[48:49]
	v_cvt_pk_bf16_f32 v32, v32, v33
	v_cvt_pk_bf16_f32 v33, v34, v35
	v_xad_u32 v48, v72, 64, v65
	ds_write_b64 v48, v[32:33]
	v_pk_mul_f32 v[32:33], v[36:37], v[64:65] op_sel_hi:[1,0]
	v_pk_mul_f32 v[34:35], v[38:39], v[64:65] op_sel_hi:[1,0]
	v_and_b32_e32 v69, 56, v141
	v_cvt_pk_bf16_f32 v32, v32, v33
	v_cvt_pk_bf16_f32 v33, v34, v35
	v_xad_u32 v49, v72, s0, v65
	v_lshlrev_b32_e32 v96, 1, v69
	v_lshrrev_b32_e32 v69, 3, v144
	ds_write_b64 v49, v[32:33]
	v_pk_mul_f32 v[32:33], v[40:41], v[64:65] op_sel_hi:[1,0]
	v_pk_mul_f32 v[34:35], v[42:43], v[64:65] op_sel_hi:[1,0]
	s_movk_i32 s0, 0x60
	v_xor_b32_e32 v71, v69, v144
	v_cvt_pk_bf16_f32 v32, v32, v33
	v_cvt_pk_bf16_f32 v33, v34, v35
	v_xad_u32 v51, v72, s0, v65
	v_lshlrev_b32_e32 v71, 4, v71
	ds_write_b64 v51, v[32:33]
	v_pk_mul_f32 v[32:33], v[44:45], v[64:65] op_sel_hi:[1,0]
	v_pk_mul_f32 v[34:35], v[46:47], v[64:65] op_sel_hi:[1,0]
	s_movk_i32 s0, 0x70
	v_lshlrev_b32_e32 v70, 7, v69
	v_and_b32_e32 v71, 0x70, v71
	v_cvt_pk_bf16_f32 v32, v32, v33
	v_cvt_pk_bf16_f32 v33, v34, v35
	v_xad_u32 v44, v72, s0, v65
	v_add3_u32 v70, v68, v70, v71
	ds_write_b64 v44, v[32:33]
	ds_read_b128 v[32:35], v70
	v_lshl_add_u64 v[66:67], v[66:67], 0, v[96:97]
	v_lshlrev_b32_e32 v96, 11, v69
	v_lshl_add_u64 v[36:37], v[66:67], 0, v[96:97]
	v_or_b32_e32 v38, 8, v69
	s_waitcnt lgkmcnt(0)
	global_store_dwordx4 v[36:37], v[32:35], off nt
	v_lshlrev_b32_e32 v96, 11, v38
	v_or_b32_e32 v40, 16, v69
	v_lshlrev_b32_e32 v32, 7, v38
	v_add3_u32 v45, v68, v32, v71
	ds_read_b128 v[32:35], v45
	v_lshl_add_u64 v[38:39], v[66:67], 0, v[96:97]
	v_lshlrev_b32_e32 v96, 11, v40
	v_or_b32_e32 v42, 24, v69
	v_pk_mul_f32 v[16:17], v[16:17], v[64:65] op_sel_hi:[1,0]
	s_waitcnt lgkmcnt(0)
	global_store_dwordx4 v[38:39], v[32:35], off nt
	v_pk_mul_f32 v[18:19], v[18:19], v[64:65] op_sel_hi:[1,0]
	v_cvt_pk_bf16_f32 v16, v16, v17
	v_lshlrev_b32_e32 v32, 7, v40
	v_add3_u32 v46, v68, v32, v71
	ds_read_b128 v[32:35], v46
	v_lshl_add_u64 v[40:41], v[66:67], 0, v[96:97]
	v_cvt_pk_bf16_f32 v17, v18, v19
	v_pk_mul_f32 v[18:19], v[22:23], v[64:65] op_sel_hi:[1,0]
	v_pk_mul_f32 v[0:1], v[0:1], v[64:65] op_sel_hi:[1,0]
	s_waitcnt lgkmcnt(0)
	global_store_dwordx4 v[40:41], v[32:35], off nt
	v_pk_mul_f32 v[2:3], v[2:3], v[64:65] op_sel_hi:[1,0]
	v_cvt_pk_bf16_f32 v0, v0, v1
	v_lshlrev_b32_e32 v32, 7, v42
	v_add3_u32 v47, v68, v32, v71
	ds_read_b128 v[32:35], v47
	ds_write_b64 v73, v[16:17]
	v_pk_mul_f32 v[16:17], v[20:21], v[64:65] op_sel_hi:[1,0]
	v_cvt_pk_bf16_f32 v1, v2, v3
	v_cvt_pk_bf16_f32 v16, v16, v17
	v_cvt_pk_bf16_f32 v17, v18, v19
	ds_write_b64 v52, v[16:17]
	v_pk_mul_f32 v[16:17], v[24:25], v[64:65] op_sel_hi:[1,0]
	v_pk_mul_f32 v[18:19], v[26:27], v[64:65] op_sel_hi:[1,0]
	v_cvt_pk_bf16_f32 v16, v16, v17
	v_cvt_pk_bf16_f32 v17, v18, v19
	ds_write_b64 v53, v[16:17]
	v_pk_mul_f32 v[16:17], v[28:29], v[64:65] op_sel_hi:[1,0]
	v_pk_mul_f32 v[18:19], v[30:31], v[64:65] op_sel_hi:[1,0]
	v_cvt_pk_bf16_f32 v16, v16, v17
	v_cvt_pk_bf16_f32 v17, v18, v19
	ds_write_b64 v50, v[16:17]
	ds_write_b64 v48, v[0:1]
	v_pk_mul_f32 v[0:1], v[4:5], v[64:65] op_sel_hi:[1,0]
	v_pk_mul_f32 v[2:3], v[6:7], v[64:65] op_sel_hi:[1,0]
	v_cvt_pk_bf16_f32 v0, v0, v1
	v_cvt_pk_bf16_f32 v1, v2, v3
	ds_write_b64 v49, v[0:1]
	v_pk_mul_f32 v[0:1], v[8:9], v[64:65] op_sel_hi:[1,0]
	v_pk_mul_f32 v[2:3], v[10:11], v[64:65] op_sel_hi:[1,0]
	v_cvt_pk_bf16_f32 v0, v0, v1
	v_cvt_pk_bf16_f32 v1, v2, v3
	ds_write_b64 v51, v[0:1]
	v_pk_mul_f32 v[0:1], v[12:13], v[64:65] op_sel_hi:[1,0]
	v_pk_mul_f32 v[2:3], v[14:15], v[64:65] op_sel_hi:[1,0]
	v_cvt_pk_bf16_f32 v0, v0, v1
	v_cvt_pk_bf16_f32 v1, v2, v3
	ds_write_b64 v44, v[0:1]
	ds_read_b128 v[0:3], v70
	ds_read_b128 v[4:7], v45
	ds_read_b128 v[8:11], v46
	ds_read_b128 v[12:15], v47
	v_lshlrev_b32_e32 v96, 11, v42
	v_lshl_add_u64 v[42:43], v[66:67], 0, v[96:97]
	s_waitcnt lgkmcnt(12)
	global_store_dwordx4 v[42:43], v[32:35], off nt
	s_waitcnt lgkmcnt(3)
	global_store_dwordx4 v[36:37], v[0:3], off offset:128 nt
	s_waitcnt lgkmcnt(2)
	global_store_dwordx4 v[38:39], v[4:7], off offset:128 nt
	s_waitcnt lgkmcnt(1)
	global_store_dwordx4 v[40:41], v[8:11], off offset:128 nt
	s_waitcnt lgkmcnt(0)
	global_store_dwordx4 v[42:43], v[12:15], off offset:128 nt
	s_cbranch_scc1 .LBB0_49
.LBB0_53:
	s_add_i32 s0, s2, 0xffffff00
	s_cmpk_lt_i32 s2, 0x100
	s_cselect_b32 s0, s2, s0
	s_and_b32 s1, s0, 7
	s_xor_b32 s4, s1, 15
	s_cmpk_lt_i32 s2, 0x100
	s_cselect_b32 s4, s4, s1
	s_ashr_i32 s0, s0, 3
	s_ashr_i32 s1, s0, 31
	s_lshr_b32 s1, s1, 29
	s_add_i32 s1, s0, s1
	s_ashr_i32 s36, s1, 3
	v_mov_b32_e32 v143, v245
	s_and_b32 s1, s1, 0x1fffff8
	s_ashr_i32 s37, s36, 31
	s_sub_i32 s8, s0, s1
	v_ashrrev_i32_e32 v145, 6, v143
	s_lshl_b64 s[0:1], s[36:37], 12
	s_lshl_b32 s5, s4, 8
	v_lshlrev_b32_e32 v140, 5, v145
	s_or_b32 s0, s0, s5
	s_lshl_b64 s[6:7], s[36:37], 23
	v_ashrrev_i32_e32 v141, 31, v140
	s_add_u32 s10, s24, s6
	v_lshl_add_u64 v[130:131], s[0:1], 0, v[140:141]
	s_addc_u32 s11, s25, s7
	s_lshl_b32 s0, s8, 7
	s_ashr_i32 s1, s0, 31
	s_lshl_b64 s[8:9], s[0:1], 1
	s_add_u32 s33, s10, s8
	s_addc_u32 s74, s11, s9
	s_add_u32 s6, s26, s6
	s_addc_u32 s7, s27, s7
	s_add_u32 s30, s6, s8
	s_addc_u32 s31, s7, s9
	s_lshl_b32 s6, s4, 19
	s_add_u32 s10, s33, s6
	s_addc_u32 s11, s74, 0
	v_readfirstlane_b32 s7, v145
	s_add_u32 s12, s30, s6
	s_addc_u32 s13, s31, 0
	s_lshl_b32 s14, s7, 3
	v_bfe_u32 v8, v143, 4, 2
	v_and_b32_e32 v144, 63, v143
	s_waitcnt lgkmcnt(0)
	v_or_b32_e32 v18, s14, v8
	v_bitop3_b32 v9, s14, v143, v8 bitop3:0x36
	v_lshlrev_b32_e32 v2, 5, v8
	v_lshlrev_b32_e32 v141, 3, v144
	s_movk_i32 s15, 0x78
	v_ashrrev_i32_e32 v19, 31, v18
	v_lshlrev_b32_e32 v9, 3, v9
	v_bitop3_b32 v2, v2, v141, s15 bitop3:0x78
	v_lshlrev_b64 v[4:5], 11, v[18:19]
	v_and_b32_e32 v9, 0x78, v9
	s_lshl_b32 s75, s7, 11
	v_lshlrev_b32_e32 v16, 1, v2
	v_mov_b32_e32 v17, v97
	v_lshl_add_u64 v[6:7], s[10:11], 0, v[4:5]
	v_lshlrev_b32_e32 v96, 1, v9
	s_add_i32 s7, s75, 0
	v_lshl_add_u64 v[2:3], s[12:13], 0, v[16:17]
	v_lshl_add_u64 v[6:7], v[6:7], 0, v[96:97]
	s_mov_b32 s12, m0
	s_mov_b32 m0, s7
	s_nop 0
	global_load_lds_dwordx4 v[6:7], off
	s_mov_b32 m0, s12
	s_add_i32 s7, 0, 0x4000
	s_add_i32 s12, s75, s7
	v_lshl_add_u64 v[6:7], v[2:3], 0, v[4:5]
	s_mov_b32 s13, m0
	s_mov_b32 m0, s12
	s_nop 0
	global_load_lds_dwordx4 v[6:7], off
	s_mov_b32 m0, s13
	s_or_b32 s12, s14, 4
	v_or_b32_e32 v20, s12, v8
	v_bitop3_b32 v10, s12, v143, v8 bitop3:0x36
	v_ashrrev_i32_e32 v21, 31, v20
	v_lshlrev_b32_e32 v10, 3, v10
	v_lshlrev_b64 v[6:7], 11, v[20:21]
	v_and_b32_e32 v10, 0x78, v10
	v_lshl_add_u64 v[8:9], s[10:11], 0, v[6:7]
	v_lshlrev_b32_e32 v132, 1, v10
	v_mov_b32_e32 v133, v97
	s_lshl_b32 s76, s12, 8
	v_lshl_add_u64 v[8:9], v[8:9], 0, v[132:133]
	s_add_i32 s10, s76, 0
	s_mov_b32 s11, m0
	s_mov_b32 m0, s10
	s_nop 0
	global_load_lds_dwordx4 v[8:9], off
	s_mov_b32 m0, s11
	s_add_i32 s7, s76, s7
	v_lshl_add_u64 v[2:3], v[2:3], 0, v[6:7]
	s_mov_b32 s10, m0
	s_mov_b32 m0, s7
	s_nop 0
	global_load_lds_dwordx4 v[2:3], off
	s_mov_b32 m0, s10
	s_or_b32 s7, s6, 0x20000
	s_add_u32 s10, s33, s7
	s_addc_u32 s11, s74, 0
	s_add_u32 s12, s30, s7
	s_addc_u32 s13, s31, 0
	v_and_b32_e32 v164, 31, v143
	v_lshl_add_u64 v[2:3], s[12:13], 0, v[16:17]
	v_lshl_add_u64 v[8:9], s[10:11], 0, v[4:5]
	v_or_b32_e32 v0, v130, v164
	v_mov_b32_e32 v1, v131
	v_lshl_add_u64 v[8:9], v[8:9], 0, v[96:97]
	s_add_i32 s7, s75, s18
	s_mov_b32 s12, m0
	s_mov_b32 m0, s7
	s_nop 0
	global_load_lds_dwordx4 v[8:9], off
	s_mov_b32 m0, s12
	v_lshl_add_u64 v[4:5], v[2:3], 0, v[4:5]
	s_add_i32 s7, s75, s19
	s_mov_b32 s12, m0
	s_mov_b32 m0, s7
	s_nop 0
	global_load_lds_dwordx4 v[4:5], off
	s_mov_b32 m0, s12
	v_lshl_add_u64 v[4:5], s[10:11], 0, v[6:7]
	v_lshlrev_b64 v[0:1], 11, v[0:1]
	v_bfe_u32 v22, v143, 5, 1
	v_lshl_add_u64 v[4:5], v[4:5], 0, v[132:133]
	s_add_i32 s7, s76, s18
	s_mov_b32 s10, m0
	s_mov_b32 m0, s7
	s_nop 0
	global_load_lds_dwordx4 v[4:5], off
	s_mov_b32 m0, s10
	v_lshl_add_u64 v[2:3], v[2:3], 0, v[6:7]
	v_lshl_add_u64 v[0:1], s[82:83], 0, v[0:1]
	s_add_i32 s7, s76, s19
	s_mov_b32 s10, m0
	s_mov_b32 m0, s7
	s_nop 0
	global_load_lds_dwordx4 v[2:3], off
	s_mov_b32 m0, s10
	v_lshl_add_u64 v[0:1], v[0:1], 0, s[8:9]
	v_lshlrev_b32_e32 v2, 4, v22
	v_mov_b32_e32 v3, v97
	v_lshl_add_u64 v[0:1], v[0:1], 0, v[2:3]
	global_load_dwordx4 v[98:101], v[0:1], off
	global_load_dwordx4 v[102:105], v[0:1], off offset:32
	global_load_dwordx4 v[106:109], v[0:1], off offset:64
	global_load_dwordx4 v[110:113], v[0:1], off offset:96
	global_load_dwordx4 v[114:117], v[0:1], off offset:128
	global_load_dwordx4 v[118:121], v[0:1], off offset:160
	global_load_dwordx4 v[122:125], v[0:1], off offset:192
	global_load_dwordx4 v[126:129], v[0:1], off offset:224
	s_cmp_lg_u32 s4, 0
	v_and_b32_e32 v23, 15, v143
	v_lshlrev_b32_e32 v17, 2, v22
	s_cbranch_scc0 .LBB0_91
	v_lshl_or_b32 v0, s36, 4, v23
	v_ashrrev_i32_e32 v1, 31, v0
	v_readlane_b32 s8, v252, 28
	v_lshlrev_b64 v[0:1], 13, v[0:1]
	v_readlane_b32 s9, v252, 29
	v_lshlrev_b32_e32 v2, 4, v145
	v_lshlrev_b32_e32 v4, 3, v22
	v_lshl_add_u64 v[0:1], s[8:9], 0, v[0:1]
	v_lshl_add_u64 v[0:1], s[0:1], 2, v[0:1]
	v_ashrrev_i32_e32 v3, 31, v2
	v_lshl_add_u64 v[0:1], v[2:3], 2, v[0:1]
	v_lshlrev_b32_e32 v2, 2, v4
	v_mov_b32_e32 v3, v97
	v_lshl_add_u64 v[8:9], v[0:1], 0, v[2:3]
	s_mov_b64 s[8:9], 0x1000
	s_movk_i32 s7, 0x1000
	global_load_dwordx4 v[0:3], v[8:9], off offset:16
	global_load_dwordx4 v[4:7], v[8:9], off
	v_lshl_add_u64 v[12:13], v[8:9], 0, s[8:9]
	v_add_co_u32_e32 v8, vcc, s7, v8
	s_mov_b32 s8, 0x3b800000
	s_nop 0
	v_addc_co_u32_e32 v9, vcc, 0, v9, vcc
	global_load_dwordx4 v[8:11], v[8:9], off
	s_nop 0
	global_load_dwordx4 v[12:15], v[12:13], off offset:16
	v_cmp_gt_u32_e32 vcc, 16, v164
	v_lshl_add_u32 v28, v144, 4, s77
	v_lshlrev_b32_e32 v146, 2, v22
	v_cmp_gt_u32_e64 s[36:37], s4, v146
	s_movk_i32 s7, 0x100
	s_waitcnt vmcnt(0)
	v_pk_add_f32 v[6:7], v[6:7], v[10:11]
	v_pk_add_f32 v[4:5], v[4:5], v[8:9]
	v_pk_mul_f32 v[8:9], v[6:7], s[8:9] op_sel_hi:[1,0]
	v_pk_mul_f32 v[10:11], v[4:5], s[8:9] op_sel_hi:[1,0]
	s_waitcnt vmcnt(0)
	v_pk_add_f32 v[2:3], v[2:3], v[14:15]
	v_pk_add_f32 v[0:1], v[0:1], v[12:13]
	v_cvt_pk_bf16_f32 v10, v10, v11
	v_cvt_pk_bf16_f32 v11, v8, v9
	v_pk_mul_f32 v[12:13], v[2:3], s[8:9] op_sel_hi:[1,0]
	v_pk_mul_f32 v[14:15], v[0:1], s[8:9] op_sel_hi:[1,0]
	v_lshlrev_b32_e32 v8, 16, v11
	v_and_b32_e32 v9, 0xffff0000, v11
	v_cvt_pk_bf16_f32 v14, v14, v15
	v_cvt_pk_bf16_f32 v12, v12, v13
	v_lshlrev_b32_e32 v13, 16, v10
	v_and_b32_e32 v15, 0xffff0000, v10
	v_xor_b32_e32 v9, 0x80000000, v9
	v_xor_b32_e32 v8, 0x80000000, v8
	v_lshlrev_b32_e32 v26, 16, v12
	v_and_b32_e32 v27, 0xffff0000, v12
	v_pk_fma_f32 v[6:7], v[6:7], s[8:9], v[8:9] op_sel_hi:[1,0,1]
	v_xor_b32_e32 v9, 0x80000000, v15
	v_xor_b32_e32 v8, 0x80000000, v13
	v_lshlrev_b32_e32 v24, 16, v14
	v_and_b32_e32 v25, 0xffff0000, v14
	v_pk_fma_f32 v[4:5], v[4:5], s[8:9], v[8:9] op_sel_hi:[1,0,1]
	v_xor_b32_e32 v9, 0x80000000, v27
	v_xor_b32_e32 v8, 0x80000000, v26
	v_pk_fma_f32 v[2:3], v[2:3], s[8:9], v[8:9] op_sel_hi:[1,0,1]
	v_xor_b32_e32 v9, 0x80000000, v25
	v_xor_b32_e32 v8, 0x80000000, v24
	v_pk_fma_f32 v[0:1], v[0:1], s[8:9], v[8:9] op_sel_hi:[1,0,1]
	v_cvt_pk_bf16_f32 v4, v4, v5
	v_cvt_pk_bf16_f32 v5, v6, v7
	v_cvt_pk_bf16_f32 v0, v0, v1
	v_cvt_pk_bf16_f32 v1, v2, v3
	v_cndmask_b32_e32 v3, v1, v12, vcc
	v_cndmask_b32_e32 v1, v5, v11, vcc
	v_cndmask_b32_e32 v2, v0, v14, vcc
	v_cndmask_b32_e32 v0, v4, v10, vcc
	v_lshl_add_u32 v4, v143, 4, s77
	ds_write_b128 v4, v[0:3]
	s_waitcnt lgkmcnt(0)
	s_barrier
	ds_read_b128 v[32:35], v28
	ds_read_b128 v[36:39], v28 offset:1024
	ds_read_b128 v[40:43], v28 offset:2048
	ds_read_b128 v[44:47], v28 offset:3072
	ds_read_b128 v[48:51], v28 offset:4096
	ds_read_b128 v[52:55], v28 offset:5120
	ds_read_b128 v[56:59], v28 offset:6144
	ds_read_b128 v[60:63], v28 offset:7168
	s_waitcnt lgkmcnt(7)
	v_mfma_f32_32x32x16_bf16 v[0:15], v[32:35], v[98:101], 0
	v_cmp_lt_i32_e32 vcc, v234, v228
	s_waitcnt lgkmcnt(6)
	v_mfma_f32_32x32x16_bf16 v[0:15], v[36:39], v[102:105], v[0:15]
	s_waitcnt lgkmcnt(5)
	v_mfma_f32_32x32x16_bf16 v[0:15], v[40:43], v[106:109], v[0:15]
	s_waitcnt lgkmcnt(4)
	v_mfma_f32_32x32x16_bf16 v[0:15], v[44:47], v[110:113], v[0:15]
	s_waitcnt lgkmcnt(3)
	v_mfma_f32_32x32x16_bf16 v[0:15], v[48:51], v[114:117], v[0:15]
	s_waitcnt lgkmcnt(2)
	v_mfma_f32_32x32x16_bf16 v[0:15], v[52:55], v[118:121], v[0:15]
	s_waitcnt lgkmcnt(1)
	v_mfma_f32_32x32x16_bf16 v[0:15], v[56:59], v[122:125], v[0:15]
	s_waitcnt lgkmcnt(0)
	v_mfma_f32_32x32x16_bf16 v[0:15], v[60:63], v[126:129], v[0:15]
	s_nop 11
	v_add_f32_e32 v25, v0, v8
	v_add_f32_e32 v8, v3, v11
	v_add_f32_e32 v3, v4, v12
	v_cndmask_b32_e32 v4, v227, v234, vcc
	v_lshlrev_b32_e32 v4, 2, v4
	v_add_f32_e32 v24, v1, v9
	v_add_f32_e32 v9, v2, v10
	v_add_f32_e32 v2, v5, v13
	v_cndmask_b32_e64 v26, v235, v25, s[36:37]
	v_add_f32_e32 v1, v6, v14
	v_xor_b32_e32 v14, 4, v146
	v_add_f32_e32 v0, v7, v15
	ds_bpermute_b32 v13, v4, v25
	ds_bpermute_b32 v12, v4, v24
	ds_bpermute_b32 v11, v4, v9
	ds_bpermute_b32 v10, v4, v8
	ds_bpermute_b32 v7, v4, v3
	ds_bpermute_b32 v6, v4, v2
	ds_bpermute_b32 v5, v4, v1
	ds_bpermute_b32 v4, v4, v0
	s_waitcnt lgkmcnt(7)
	v_cmp_nlt_f32_e64 s[38:39], v26, v13
	s_and_b64 s[38:39], s[36:37], s[38:39]
	v_cndmask_b32_e64 v15, -1, v146, s[36:37]
	v_cmp_gt_u32_e32 vcc, s4, v14
	v_cndmask_b32_e64 v27, v14, v146, s[38:39]
	v_cndmask_b32_e64 v28, v13, v25, s[38:39]
	v_cndmask_b32_e32 v27, v15, v27, vcc
	v_cndmask_b32_e32 v28, v26, v28, vcc
	v_or_b32_e32 v26, 1, v146
	v_cmp_gt_i32_e64 s[38:39], 0, v27
	v_cmp_gt_f32_e64 s[42:43], v24, v28
	v_cmp_gt_u32_e64 s[40:41], s4, v26
	s_or_b64 s[8:9], s[38:39], s[42:43]
	s_and_b64 s[38:39], s[40:41], s[8:9]
	v_cndmask_b32_e64 v27, v27, v26, s[38:39]
	v_cndmask_b32_e64 v28, v28, v24, s[38:39]
	v_xor_b32_e32 v15, 5, v146
	v_cmp_gt_i32_e64 s[42:43], 0, v27
	s_waitcnt lgkmcnt(6)
	v_cmp_lt_f32_e64 s[44:45], v28, v12
	v_cmp_gt_u32_e64 s[38:39], s4, v15
	s_or_b64 s[8:9], s[42:43], s[44:45]
	s_and_b64 s[42:43], s[38:39], s[8:9]
	v_cndmask_b32_e64 v29, v27, v15, s[42:43]
	v_cndmask_b32_e64 v30, v28, v12, s[42:43]
	v_or_b32_e32 v28, 2, v146
	v_cmp_gt_i32_e64 s[42:43], 0, v29
	v_cmp_gt_f32_e64 s[46:47], v9, v30
	v_cmp_gt_u32_e64 s[44:45], s4, v28
	s_or_b64 s[8:9], s[42:43], s[46:47]
	s_and_b64 s[42:43], s[44:45], s[8:9]
	v_cndmask_b32_e64 v29, v29, v28, s[42:43]
	v_cndmask_b32_e64 v30, v30, v9, s[42:43]
	v_xor_b32_e32 v27, 6, v146
	v_cmp_gt_i32_e64 s[46:47], 0, v29
	s_waitcnt lgkmcnt(5)
	v_cmp_lt_f32_e64 s[48:49], v30, v11
	v_cmp_gt_u32_e64 s[42:43], s4, v27
	s_or_b64 s[8:9], s[46:47], s[48:49]
	s_and_b64 s[46:47], s[42:43], s[8:9]
	v_cndmask_b32_e64 v31, v29, v27, s[46:47]
	v_cndmask_b32_e64 v32, v30, v11, s[46:47]
	v_or_b32_e32 v30, 3, v146
	v_cmp_gt_i32_e64 s[46:47], 0, v31
	v_cmp_gt_f32_e64 s[50:51], v8, v32
	v_cmp_gt_u32_e64 s[48:49], s4, v30
	s_or_b64 s[8:9], s[46:47], s[50:51]
	s_and_b64 s[46:47], s[48:49], s[8:9]
	v_cndmask_b32_e64 v31, v31, v30, s[46:47]
	v_cndmask_b32_e64 v32, v32, v8, s[46:47]
	v_xor_b32_e32 v29, 7, v146
	v_cmp_gt_i32_e64 s[50:51], 0, v31
	s_waitcnt lgkmcnt(4)
	v_cmp_lt_f32_e64 s[52:53], v32, v10
	v_cmp_gt_u32_e64 s[46:47], s4, v29
	s_or_b64 s[8:9], s[50:51], s[52:53]
	s_and_b64 s[50:51], s[46:47], s[8:9]
	v_cndmask_b32_e64 v33, v31, v29, s[50:51]
	v_cndmask_b32_e64 v34, v32, v10, s[50:51]
	v_or_b32_e32 v32, 8, v146
	v_cmp_gt_i32_e64 s[50:51], 0, v33
	v_cmp_gt_f32_e64 s[54:55], v3, v34
	v_cmp_gt_u32_e64 s[52:53], s4, v32
	s_or_b64 s[8:9], s[50:51], s[54:55]
	s_and_b64 s[50:51], s[52:53], s[8:9]
	v_cndmask_b32_e64 v33, v33, v32, s[50:51]
	v_cndmask_b32_e64 v34, v34, v3, s[50:51]
	v_xor_b32_e32 v31, 12, v146
	v_cmp_gt_i32_e64 s[54:55], 0, v33
	s_waitcnt lgkmcnt(3)
	v_cmp_lt_f32_e64 s[56:57], v34, v7
	v_cmp_gt_u32_e64 s[50:51], s4, v31
	s_or_b64 s[8:9], s[54:55], s[56:57]
	s_and_b64 s[54:55], s[50:51], s[8:9]
	v_cndmask_b32_e64 v35, v33, v31, s[54:55]
	v_cndmask_b32_e64 v36, v34, v7, s[54:55]
	v_or_b32_e32 v34, 9, v146
	v_cmp_gt_i32_e64 s[54:55], 0, v35
	v_cmp_gt_f32_e64 s[58:59], v2, v36
	v_cmp_gt_u32_e64 s[56:57], s4, v34
	s_or_b64 s[8:9], s[54:55], s[58:59]
	s_and_b64 s[54:55], s[56:57], s[8:9]
	v_cndmask_b32_e64 v35, v35, v34, s[54:55]
	v_cndmask_b32_e64 v36, v36, v2, s[54:55]
	v_xor_b32_e32 v33, 13, v146
	v_cmp_gt_i32_e64 s[58:59], 0, v35
	s_waitcnt lgkmcnt(2)
	v_cmp_lt_f32_e64 s[60:61], v36, v6
	v_cmp_gt_u32_e64 s[54:55], s4, v33
	s_or_b64 s[8:9], s[58:59], s[60:61]
	s_and_b64 s[58:59], s[54:55], s[8:9]
	v_cndmask_b32_e64 v37, v35, v33, s[58:59]
	v_cndmask_b32_e64 v38, v36, v6, s[58:59]
	v_or_b32_e32 v36, 10, v146
	v_cmp_gt_i32_e64 s[58:59], 0, v37
	v_cmp_gt_f32_e64 s[62:63], v1, v38
	v_cmp_gt_u32_e64 s[60:61], s4, v36
	s_or_b64 s[8:9], s[58:59], s[62:63]
	s_and_b64 s[58:59], s[60:61], s[8:9]
	v_cndmask_b32_e64 v37, v37, v36, s[58:59]
	v_cndmask_b32_e64 v38, v38, v1, s[58:59]
	v_xor_b32_e32 v35, 14, v146
	v_cmp_gt_i32_e64 s[62:63], 0, v37
	s_waitcnt lgkmcnt(1)
	v_cmp_lt_f32_e64 s[64:65], v38, v5
	v_cmp_gt_u32_e64 s[58:59], s4, v35
	s_or_b64 s[8:9], s[62:63], s[64:65]
	s_and_b64 s[62:63], s[58:59], s[8:9]
	v_cndmask_b32_e64 v39, v37, v35, s[62:63]
	v_cndmask_b32_e64 v40, v38, v5, s[62:63]
	v_or_b32_e32 v38, 11, v146
	v_cmp_gt_i32_e64 s[62:63], 0, v39
	v_cmp_gt_f32_e64 s[66:67], v0, v40
	v_cmp_gt_u32_e64 s[64:65], s4, v38
	s_or_b64 s[8:9], s[62:63], s[66:67]
	s_and_b64 s[62:63], s[64:65], s[8:9]
	v_cndmask_b32_e64 v39, v39, v38, s[62:63]
	v_cndmask_b32_e64 v40, v40, v0, s[62:63]
	v_xor_b32_e32 v37, 15, v146
	v_cmp_gt_i32_e64 s[66:67], 0, v39
	s_waitcnt lgkmcnt(0)
	v_cmp_lt_f32_e64 s[70:71], v40, v4
	v_cmp_gt_u32_e64 s[62:63], s4, v37
	s_or_b64 s[8:9], s[66:67], s[70:71]
	s_and_b64 s[66:67], s[62:63], s[8:9]
	v_cndmask_b32_e64 v39, v39, v37, s[66:67]
	v_lshlrev_b32_e64 v40, v39, 1
	v_cmp_lt_i32_e64 s[66:67], -1, v39
	s_nop 1
	v_cndmask_b32_e64 v39, 0, v40, s[66:67]
	v_lshlrev_b32_e64 v40, v146, 1
	v_and_b32_e32 v41, v39, v40
	v_cmp_eq_u32_e64 s[66:67], 0, v41
	s_and_b64 s[66:67], s[36:37], s[66:67]
	v_lshlrev_b32_e64 v41, v14, 1
	v_cndmask_b32_e64 v43, v235, v25, s[66:67]
	v_and_b32_e32 v44, v39, v41
	v_cmp_nlt_f32_e64 s[72:73], v43, v13
	v_cndmask_b32_e64 v42, -1, v146, s[66:67]
	v_cmp_eq_u32_e64 s[70:71], 0, v44
	s_and_b64 s[66:67], s[66:67], s[72:73]
	s_and_b64 s[70:71], vcc, s[70:71]
	v_cndmask_b32_e64 v44, v14, v42, s[66:67]
	v_cndmask_b32_e64 v45, v13, v43, s[66:67]
	v_cndmask_b32_e64 v42, v42, v44, s[70:71]
	v_lshlrev_b32_e64 v44, v146, 2
	v_cndmask_b32_e64 v43, v43, v45, s[70:71]
	v_and_b32_e32 v45, v39, v44
	v_cmp_eq_u32_e64 s[66:67], 0, v45
	s_and_b64 s[8:9], s[40:41], s[66:67]
	v_cmp_gt_i32_e64 s[66:67], 0, v42
	v_cmp_gt_f32_e64 s[70:71], v24, v43
	s_or_b64 s[10:11], s[66:67], s[70:71]
	v_lshlrev_b32_e64 v45, v15, 1
	s_and_b64 s[66:67], s[8:9], s[10:11]
	v_and_b32_e32 v46, v39, v45
	v_cndmask_b32_e64 v42, v42, v26, s[66:67]
	v_cndmask_b32_e64 v43, v43, v24, s[66:67]
	v_cmp_eq_u32_e64 s[66:67], 0, v46
	s_and_b64 s[8:9], s[38:39], s[66:67]
	v_cmp_gt_i32_e64 s[66:67], 0, v42
	v_cmp_lt_f32_e64 s[70:71], v43, v12
	s_or_b64 s[10:11], s[66:67], s[70:71]
	v_lshlrev_b32_e64 v46, v146, 4
	s_and_b64 s[66:67], s[8:9], s[10:11]
	v_and_b32_e32 v47, v39, v46
	v_cndmask_b32_e64 v42, v42, v15, s[66:67]
	v_cndmask_b32_e64 v43, v43, v12, s[66:67]
	v_cmp_eq_u32_e64 s[66:67], 0, v47
	s_and_b64 s[8:9], s[44:45], s[66:67]
	v_cmp_gt_i32_e64 s[66:67], 0, v42
	v_cmp_gt_f32_e64 s[70:71], v9, v43
	s_or_b64 s[10:11], s[66:67], s[70:71]
	v_lshlrev_b32_e64 v47, v27, 1
	s_and_b64 s[66:67], s[8:9], s[10:11]
	v_and_b32_e32 v48, v39, v47
	v_cndmask_b32_e64 v42, v42, v28, s[66:67]
	v_cndmask_b32_e64 v43, v43, v9, s[66:67]
	v_cmp_eq_u32_e64 s[66:67], 0, v48
	s_and_b64 s[8:9], s[42:43], s[66:67]
	v_cmp_gt_i32_e64 s[66:67], 0, v42
	v_cmp_lt_f32_e64 s[70:71], v43, v11
	s_or_b64 s[10:11], s[66:67], s[70:71]
	v_lshlrev_b32_e64 v48, v146, 8
	s_and_b64 s[66:67], s[8:9], s[10:11]
	v_and_b32_e32 v49, v39, v48
	v_cndmask_b32_e64 v42, v42, v27, s[66:67]
	v_cndmask_b32_e64 v43, v43, v11, s[66:67]
	v_cmp_eq_u32_e64 s[66:67], 0, v49
	s_and_b64 s[8:9], s[48:49], s[66:67]
	v_cmp_gt_i32_e64 s[66:67], 0, v42
	v_cmp_gt_f32_e64 s[70:71], v8, v43
	s_or_b64 s[10:11], s[66:67], s[70:71]
	v_lshlrev_b32_e64 v49, v29, 1
	s_and_b64 s[66:67], s[8:9], s[10:11]
	v_and_b32_e32 v50, v39, v49
	v_cndmask_b32_e64 v42, v42, v30, s[66:67]
	v_cndmask_b32_e64 v43, v43, v8, s[66:67]
	v_cmp_eq_u32_e64 s[66:67], 0, v50
	s_and_b64 s[8:9], s[46:47], s[66:67]
	v_cmp_gt_i32_e64 s[66:67], 0, v42
	v_cmp_lt_f32_e64 s[70:71], v43, v10
	s_or_b64 s[10:11], s[66:67], s[70:71]
	v_lshlrev_b32_e64 v50, v146, s7
	s_and_b64 s[66:67], s[8:9], s[10:11]
	v_and_b32_e32 v51, v39, v50
	v_cndmask_b32_e64 v42, v42, v29, s[66:67]
	v_cndmask_b32_e64 v43, v43, v10, s[66:67]
	v_cmp_eq_u32_e64 s[66:67], 0, v51
	s_and_b64 s[8:9], s[52:53], s[66:67]
	v_cmp_gt_i32_e64 s[66:67], 0, v42
	v_cmp_gt_f32_e64 s[70:71], v3, v43
	s_or_b64 s[10:11], s[66:67], s[70:71]
	v_lshlrev_b32_e64 v51, v31, 1
	s_and_b64 s[66:67], s[8:9], s[10:11]
	v_and_b32_e32 v52, v39, v51
	v_cndmask_b32_e64 v42, v42, v32, s[66:67]
	v_cndmask_b32_e64 v43, v43, v3, s[66:67]
	v_cmp_eq_u32_e64 s[66:67], 0, v52
	s_and_b64 s[8:9], s[50:51], s[66:67]
	v_cmp_gt_i32_e64 s[66:67], 0, v42
	v_cmp_lt_f32_e64 s[70:71], v43, v7
	s_movk_i32 s7, 0x200
	s_or_b64 s[10:11], s[66:67], s[70:71]
	v_lshlrev_b32_e64 v52, v146, s7
	s_and_b64 s[66:67], s[8:9], s[10:11]
	v_and_b32_e32 v53, v39, v52
	v_cndmask_b32_e64 v42, v42, v31, s[66:67]
	v_cndmask_b32_e64 v43, v43, v7, s[66:67]
	v_cmp_eq_u32_e64 s[66:67], 0, v53
	s_and_b64 s[8:9], s[56:57], s[66:67]
	v_cmp_gt_i32_e64 s[66:67], 0, v42
	v_cmp_gt_f32_e64 s[70:71], v2, v43
	s_or_b64 s[10:11], s[66:67], s[70:71]
	v_lshlrev_b32_e64 v53, v33, 1
	s_and_b64 s[66:67], s[8:9], s[10:11]
	v_and_b32_e32 v54, v39, v53
	v_cndmask_b32_e64 v42, v42, v34, s[66:67]
	v_cndmask_b32_e64 v43, v43, v2, s[66:67]
	v_cmp_eq_u32_e64 s[66:67], 0, v54
	s_and_b64 s[8:9], s[54:55], s[66:67]
	v_cmp_gt_i32_e64 s[66:67], 0, v42
	v_cmp_lt_f32_e64 s[70:71], v43, v6
	s_movk_i32 s7, 0x400
	s_or_b64 s[10:11], s[66:67], s[70:71]
	v_lshlrev_b32_e64 v54, v146, s7
	s_and_b64 s[66:67], s[8:9], s[10:11]
	v_and_b32_e32 v55, v39, v54
	v_cndmask_b32_e64 v42, v42, v33, s[66:67]
	v_cndmask_b32_e64 v43, v43, v6, s[66:67]
	v_cmp_eq_u32_e64 s[66:67], 0, v55
	s_and_b64 s[8:9], s[60:61], s[66:67]
	v_cmp_gt_i32_e64 s[66:67], 0, v42
	v_cmp_gt_f32_e64 s[70:71], v1, v43
	s_or_b64 s[10:11], s[66:67], s[70:71]
	v_lshlrev_b32_e64 v55, v35, 1
	s_and_b64 s[66:67], s[8:9], s[10:11]
	v_and_b32_e32 v56, v39, v55
	v_cndmask_b32_e64 v42, v42, v36, s[66:67]
	v_cndmask_b32_e64 v43, v43, v1, s[66:67]
	v_cmp_eq_u32_e64 s[66:67], 0, v56
	s_and_b64 s[8:9], s[58:59], s[66:67]
	v_cmp_gt_i32_e64 s[66:67], 0, v42
	v_cmp_lt_f32_e64 s[70:71], v43, v5
	s_movk_i32 s7, 0x800
	s_or_b64 s[10:11], s[66:67], s[70:71]
	v_lshlrev_b32_e64 v56, v146, s7
	s_and_b64 s[66:67], s[8:9], s[10:11]
	v_and_b32_e32 v57, v39, v56
	v_cndmask_b32_e64 v42, v42, v35, s[66:67]
	v_cndmask_b32_e64 v43, v43, v5, s[66:67]
	v_cmp_eq_u32_e64 s[66:67], 0, v57
	s_and_b64 s[8:9], s[64:65], s[66:67]
	v_cmp_gt_i32_e64 s[66:67], 0, v42
	v_cmp_gt_f32_e64 s[70:71], v0, v43
	s_or_b64 s[10:11], s[66:67], s[70:71]
	v_lshlrev_b32_e64 v57, v37, 1
	s_and_b64 s[66:67], s[8:9], s[10:11]
	v_and_b32_e32 v58, v39, v57
	v_cndmask_b32_e64 v42, v42, v38, s[66:67]
	v_cndmask_b32_e64 v43, v43, v0, s[66:67]
	v_cmp_eq_u32_e64 s[66:67], 0, v58
	s_and_b64 s[8:9], s[62:63], s[66:67]
	v_cmp_gt_i32_e64 s[66:67], 0, v42
	v_cmp_lt_f32_e64 s[70:71], v43, v4
	s_or_b64 s[10:11], s[66:67], s[70:71]
	s_and_b64 s[66:67], s[8:9], s[10:11]
	v_cndmask_b32_e64 v42, v42, v37, s[66:67]
	v_lshlrev_b32_e64 v43, v42, 1
	v_cmp_lt_i32_e64 s[66:67], -1, v42
	s_nop 1
	v_cndmask_b32_e64 v42, 0, v43, s[66:67]
	v_bitop3_b32 v40, v42, v40, v39 bitop3:0xc8
	v_cmp_eq_u32_e64 s[66:67], 0, v40
	s_and_b64 s[36:37], s[36:37], s[66:67]
	v_bitop3_b32 v41, v42, v41, v39 bitop3:0xc8
	v_cndmask_b32_e64 v25, v235, v25, s[36:37]
	v_cmp_eq_u32_e64 s[66:67], 0, v41
	s_and_b64 vcc, vcc, s[66:67]
	v_cmp_nlt_f32_e64 s[66:67], v25, v13
	v_cndmask_b32_e64 v40, -1, v146, s[36:37]
	s_and_b64 s[36:37], s[36:37], s[66:67]
	v_cndmask_b32_e64 v13, v13, v25, s[36:37]
	v_cndmask_b32_e64 v14, v14, v40, s[36:37]
	v_cndmask_b32_e32 v13, v25, v13, vcc
	v_bitop3_b32 v25, v42, v44, v39 bitop3:0xc8
	v_cndmask_b32_e32 v14, v40, v14, vcc
	v_cmp_eq_u32_e32 vcc, 0, v25
	s_and_b64 s[8:9], s[40:41], vcc
	v_cmp_gt_i32_e32 vcc, 0, v14
	v_cmp_gt_f32_e64 s[36:37], v24, v13
	s_or_b64 s[10:11], vcc, s[36:37]
	s_and_b64 vcc, s[8:9], s[10:11]
	v_cndmask_b32_e32 v13, v13, v24, vcc
	v_bitop3_b32 v24, v42, v45, v39 bitop3:0xc8
	v_cndmask_b32_e32 v14, v14, v26, vcc
	v_cmp_eq_u32_e32 vcc, 0, v24
	s_and_b64 s[8:9], s[38:39], vcc
	v_cmp_gt_i32_e32 vcc, 0, v14
	v_cmp_lt_f32_e64 s[36:37], v13, v12
	s_or_b64 s[10:11], vcc, s[36:37]
	s_and_b64 vcc, s[8:9], s[10:11]
	v_cndmask_b32_e32 v12, v13, v12, vcc
	v_bitop3_b32 v13, v42, v46, v39 bitop3:0xc8
	v_cndmask_b32_e32 v14, v14, v15, vcc
	v_cmp_eq_u32_e32 vcc, 0, v13
	s_and_b64 s[8:9], s[44:45], vcc
	v_cmp_gt_i32_e32 vcc, 0, v14
	v_cmp_gt_f32_e64 s[36:37], v9, v12
	s_or_b64 s[10:11], vcc, s[36:37]
	s_and_b64 vcc, s[8:9], s[10:11]
	v_cndmask_b32_e32 v9, v12, v9, vcc
	v_bitop3_b32 v12, v42, v47, v39 bitop3:0xc8
	v_cndmask_b32_e32 v13, v14, v28, vcc
	v_cmp_eq_u32_e32 vcc, 0, v12
	s_and_b64 s[8:9], s[42:43], vcc
	v_cmp_gt_i32_e32 vcc, 0, v13
	v_cmp_lt_f32_e64 s[36:37], v9, v11
	s_or_b64 s[10:11], vcc, s[36:37]
	s_and_b64 vcc, s[8:9], s[10:11]
	v_cndmask_b32_e32 v9, v9, v11, vcc
	v_bitop3_b32 v11, v42, v48, v39 bitop3:0xc8
	v_cndmask_b32_e32 v12, v13, v27, vcc
	v_cmp_eq_u32_e32 vcc, 0, v11
	s_and_b64 s[8:9], s[48:49], vcc
	v_cmp_gt_i32_e32 vcc, 0, v12
	v_cmp_gt_f32_e64 s[36:37], v8, v9
	s_or_b64 s[10:11], vcc, s[36:37]
	s_and_b64 vcc, s[8:9], s[10:11]
	v_cndmask_b32_e32 v8, v9, v8, vcc
	v_bitop3_b32 v9, v42, v49, v39 bitop3:0xc8
	v_cndmask_b32_e32 v11, v12, v30, vcc
	v_cmp_eq_u32_e32 vcc, 0, v9
	s_and_b64 s[8:9], s[46:47], vcc
	v_cmp_gt_i32_e32 vcc, 0, v11
	v_cmp_lt_f32_e64 s[36:37], v8, v10
	s_or_b64 s[10:11], vcc, s[36:37]
	s_and_b64 vcc, s[8:9], s[10:11]
	v_cndmask_b32_e32 v8, v8, v10, vcc
	v_bitop3_b32 v10, v42, v50, v39 bitop3:0xc8
	v_cndmask_b32_e32 v9, v11, v29, vcc
	v_cmp_eq_u32_e32 vcc, 0, v10
	s_and_b64 s[8:9], s[52:53], vcc
	v_cmp_gt_i32_e32 vcc, 0, v9
	v_cmp_gt_f32_e64 s[36:37], v3, v8
	s_or_b64 s[10:11], vcc, s[36:37]
	s_and_b64 vcc, s[8:9], s[10:11]
	v_cndmask_b32_e32 v3, v8, v3, vcc
	v_bitop3_b32 v8, v42, v51, v39 bitop3:0xc8
	v_cndmask_b32_e32 v9, v9, v32, vcc
	v_cmp_eq_u32_e32 vcc, 0, v8
	s_and_b64 s[8:9], s[50:51], vcc
	v_cmp_gt_i32_e32 vcc, 0, v9
	v_cmp_lt_f32_e64 s[36:37], v3, v7
	s_or_b64 s[10:11], vcc, s[36:37]
	s_and_b64 vcc, s[8:9], s[10:11]
	v_cndmask_b32_e32 v3, v3, v7, vcc
	v_bitop3_b32 v7, v42, v52, v39 bitop3:0xc8
	v_cndmask_b32_e32 v8, v9, v31, vcc
	v_cmp_eq_u32_e32 vcc, 0, v7
	s_and_b64 s[8:9], s[56:57], vcc
	v_cmp_gt_i32_e32 vcc, 0, v8
	v_cmp_gt_f32_e64 s[36:37], v2, v3
	s_or_b64 s[10:11], vcc, s[36:37]
	s_and_b64 vcc, s[8:9], s[10:11]
	v_cndmask_b32_e32 v2, v3, v2, vcc
	v_bitop3_b32 v3, v42, v53, v39 bitop3:0xc8
	v_cndmask_b32_e32 v7, v8, v34, vcc
	v_cmp_eq_u32_e32 vcc, 0, v3
	s_and_b64 s[8:9], s[54:55], vcc
	v_cmp_gt_i32_e32 vcc, 0, v7
	v_cmp_lt_f32_e64 s[36:37], v2, v6
	s_or_b64 s[10:11], vcc, s[36:37]
	s_and_b64 vcc, s[8:9], s[10:11]
	v_cndmask_b32_e32 v2, v2, v6, vcc
	v_bitop3_b32 v6, v42, v54, v39 bitop3:0xc8
	v_cndmask_b32_e32 v3, v7, v33, vcc
	v_cmp_eq_u32_e32 vcc, 0, v6
	s_and_b64 s[8:9], s[60:61], vcc
	v_cmp_gt_i32_e32 vcc, 0, v3
	v_cmp_gt_f32_e64 s[36:37], v1, v2
	s_or_b64 s[10:11], vcc, s[36:37]
	s_and_b64 vcc, s[8:9], s[10:11]
	v_cndmask_b32_e32 v1, v2, v1, vcc
	v_bitop3_b32 v2, v42, v55, v39 bitop3:0xc8
	v_cndmask_b32_e32 v3, v3, v36, vcc
	v_cmp_eq_u32_e32 vcc, 0, v2
	s_and_b64 s[8:9], s[58:59], vcc
	v_cmp_gt_i32_e32 vcc, 0, v3
	v_cmp_lt_f32_e64 s[36:37], v1, v5
	s_or_b64 s[10:11], vcc, s[36:37]
	s_and_b64 vcc, s[8:9], s[10:11]
	v_cndmask_b32_e32 v2, v3, v35, vcc
	v_bitop3_b32 v3, v42, v56, v39 bitop3:0xc8
	v_cndmask_b32_e32 v1, v1, v5, vcc
	v_cmp_eq_u32_e32 vcc, 0, v3
	s_and_b64 s[8:9], s[64:65], vcc
	v_cmp_gt_i32_e32 vcc, 0, v2
	v_cmp_gt_f32_e64 s[36:37], v0, v1
	s_or_b64 s[10:11], vcc, s[36:37]
	s_and_b64 vcc, s[8:9], s[10:11]
	v_cndmask_b32_e32 v0, v1, v0, vcc
	v_bitop3_b32 v1, v42, v57, v39 bitop3:0xc8
	v_cndmask_b32_e32 v2, v2, v38, vcc
	v_cmp_eq_u32_e32 vcc, 0, v1
	s_and_b64 s[8:9], s[62:63], vcc
	v_cmp_gt_i32_e32 vcc, 0, v2
	v_cmp_lt_f32_e64 s[36:37], v0, v4
	s_or_b64 s[10:11], vcc, s[36:37]
	s_and_b64 vcc, s[8:9], s[10:11]
	v_cndmask_b32_e32 v0, v2, v37, vcc
	v_lshlrev_b32_e64 v1, v0, 1
	v_cmp_lt_i32_e32 vcc, -1, v0
	v_or_b32_e32 v43, v42, v39
	v_readlane_b32 s45, v251, 17
	v_cndmask_b32_e32 v0, 0, v1, vcc
	s_movk_i32 s44, 0xc0
	v_or_b32_e32 v147, v0, v43
	s_cbranch_execnz .LBB0_56
